# ph0 scaled weight-transpose items (w_uk/w_uv/w_uq): 16 loads per iteration in flight instead of 1-2; on top of v41
# speedup vs baseline: 1.0030x; 1.0030x over previous
.LBB0_45:
	global_load_dword v120, v[8:9], off
	v_lshl_add_u64 v[136:137], v[6:7], 0, s[4:5]
	global_load_dword v128, v[136:137], off
	v_lshl_add_u64 v[138:139], v[4:5], 0, s[4:5]
	v_add_u32_e32 v18, 0x1800, v2
	v_lshl_add_u64 v[136:137], v[18:19], 2, v[0:1]
	global_load_dword v121, v[136:137], off
	global_load_dword v129, v[138:139], off offset:8
	v_add_u32_e32 v18, 0x3000, v2
	v_lshl_add_u64 v[136:137], v[18:19], 2, v[0:1]
	global_load_dword v122, v[136:137], off
	global_load_dword v130, v[138:139], off offset:16
	v_add_u32_e32 v18, 0x4800, v2
	v_lshl_add_u64 v[136:137], v[18:19], 2, v[0:1]
	global_load_dword v123, v[136:137], off
	global_load_dword v131, v[138:139], off offset:24
	v_add_u32_e32 v18, 0x6000, v2
	v_lshl_add_u64 v[136:137], v[18:19], 2, v[0:1]
	global_load_dword v124, v[136:137], off
	global_load_dword v132, v[138:139], off offset:32
	v_add_u32_e32 v18, 0x7800, v2
	v_lshl_add_u64 v[136:137], v[18:19], 2, v[0:1]
	global_load_dword v125, v[136:137], off
	global_load_dword v133, v[138:139], off offset:40
	v_add_u32_e32 v18, 0x9000, v2
	v_lshl_add_u64 v[136:137], v[18:19], 2, v[0:1]
	global_load_dword v126, v[136:137], off
	global_load_dword v134, v[138:139], off offset:48
	v_add_u32_e32 v18, 0xa800, v2
	v_lshl_add_u64 v[136:137], v[18:19], 2, v[0:1]
	global_load_dword v127, v[136:137], off
	global_load_dword v135, v[138:139], off offset:56
	s_waitcnt vmcnt(0)
	v_mul_f32_e32 v120, v120, v128
	v_mul_f32_e32 v121, v121, v129
	v_mul_f32_e32 v122, v122, v130
	v_mul_f32_e32 v123, v123, v131
	v_mul_f32_e32 v124, v124, v132
	v_mul_f32_e32 v125, v125, v133
	v_mul_f32_e32 v126, v126, v134
	v_mul_f32_e32 v127, v127, v135
	ds_write_b32 v3, v120
	ds_write_b32 v3, v121 offset:264
	ds_write_b32 v3, v122 offset:528
	ds_write_b32 v3, v123 offset:792
	ds_write_b32 v3, v124 offset:1056
	ds_write_b32 v3, v125 offset:1320
	ds_write_b32 v3, v126 offset:1584
	ds_write_b32 v3, v127 offset:1848
	s_add_u32 s4, s4, 64
	s_addc_u32 s5, s5, 0
	s_mov_b64 s[0:1], 0x30000
	v_add_u32_e32 v3, 0x840, v3
	v_add_u32_e32 v2, 0xc000, v2
	s_cmpk_lg_i32 s4, 0x100
	v_lshl_add_u64 v[8:9], v[8:9], 0, s[0:1]
	s_cbranch_scc1 .LBB0_45

.LBB0_66:
	v_lshl_add_u64 v[136:137], v[88:89], 0, s[2:3]
	global_load_dword v120, v[136:137], off
	v_lshl_add_u64 v[136:137], s[4:5], 0, v[18:19]
	global_load_dword v128, v[136:137], off
	v_lshl_add_u64 v[138:139], s[4:5], 0, v[0:1]
	v_lshl_add_u64 v[136:137], v[14:15], 0, s[2:3]
	global_load_dword v121, v[136:137], off
	global_load_dword v129, v[138:139], off offset:8
	v_lshl_add_u64 v[136:137], v[12:13], 0, s[2:3]
	global_load_dword v122, v[136:137], off
	global_load_dword v130, v[138:139], off offset:16
	v_lshl_add_u64 v[136:137], v[10:11], 0, s[2:3]
	global_load_dword v123, v[136:137], off
	global_load_dword v131, v[138:139], off offset:24
	v_lshl_add_u64 v[136:137], v[8:9], 0, s[2:3]
	global_load_dword v124, v[136:137], off
	global_load_dword v132, v[138:139], off offset:32
	v_lshl_add_u64 v[136:137], v[6:7], 0, s[2:3]
	global_load_dword v125, v[136:137], off
	global_load_dword v133, v[138:139], off offset:40
	v_lshl_add_u64 v[136:137], v[4:5], 0, s[2:3]
	global_load_dword v126, v[136:137], off
	global_load_dword v134, v[138:139], off offset:48
	v_lshl_add_u64 v[136:137], v[2:3], 0, s[2:3]
	global_load_dword v127, v[136:137], off
	global_load_dword v135, v[138:139], off offset:56
	s_waitcnt vmcnt(0)
	v_mul_f32_e32 v120, v120, v128
	v_mul_f32_e32 v121, v121, v129
	v_mul_f32_e32 v122, v122, v130
	v_mul_f32_e32 v123, v123, v131
	v_mul_f32_e32 v124, v124, v132
	v_mul_f32_e32 v125, v125, v133
	v_mul_f32_e32 v126, v126, v134
	v_mul_f32_e32 v127, v127, v135
	ds_write_b32 v73, v120
	ds_write_b32 v73, v121 offset:264
	ds_write_b32 v73, v122 offset:528
	ds_write_b32 v73, v123 offset:792
	ds_write_b32 v73, v124 offset:1056
	ds_write_b32 v73, v125 offset:1320
	ds_write_b32 v73, v126 offset:1584
	ds_write_b32 v73, v127 offset:1848
	s_add_u32 s2, s2, 0x20000
	s_addc_u32 s3, s3, 0
	s_add_u32 s4, s4, 64
	s_addc_u32 s5, s5, 0
	s_cmp_lg_u32 s2, 0x80000
	v_add_u32_e32 v73, 0x840, v73
	s_cbranch_scc1 .LBB0_66
